# v14 + GEMM loops: fragment ds_reads interleaved one-per-MFMA in phases P1-P3 (MFMA/LDS interleave)
# speedup vs baseline: 1.0003x; 1.0003x over previous
.Lgm_loop_B:
	ds_read_b128 v[112:115], v213 offset:0
	ds_read_b128 v[116:119], v213 offset:4096
	ds_read_b128 v[120:123], v217 offset:32768
	ds_read_b128 v[124:127], v217 offset:36864
	s_waitcnt lgkmcnt(12)
	v_mfma_f32_32x32x16_bf16 v[48:63], v[64:67], v[72:75], v[48:63]
	v_mfma_f32_32x32x16_bf16 v[32:47], v[64:67], v[76:79], v[32:47]
	v_mfma_f32_32x32x16_bf16 v[16:31], v[68:71], v[72:75], v[16:31]
	v_mfma_f32_32x32x16_bf16 v[0:15], v[68:71], v[76:79], v[0:15]
	s_waitcnt vmcnt(0) lgkmcnt(0)
	s_barrier
	s_cmp_lt_u32 s64, 30
	s_cbranch_scc0 .Lgm_nodma0_B
	s_add_u32 m0, s65, 0x0
	s_nop 0
	global_load_lds_dwordx4 v206, s[68:69]
	s_add_u32 m0, s65, 0x1000
	s_nop 0
	global_load_lds_dwordx4 v207, s[68:69]
	s_add_u32 m0, s65, 0x2000
	s_nop 0
	global_load_lds_dwordx4 v208, s[68:69]
	s_add_u32 m0, s65, 0x3000
	s_nop 0
	global_load_lds_dwordx4 v209, s[68:69]
	s_add_u32 m0, s65, 0x8000
	s_nop 0
	global_load_lds_dwordx4 v206, s[70:71]
	s_add_u32 m0, s65, 0x9000
	s_nop 0
	global_load_lds_dwordx4 v207, s[70:71]
	s_add_u32 m0, s65, 0xa000
	s_nop 0
	global_load_lds_dwordx4 v208, s[70:71]
	s_add_u32 m0, s65, 0xb000
	s_nop 0
	global_load_lds_dwordx4 v209, s[70:71]
	s_add_u32 s68, s68, 0x80
	s_addc_u32 s69, s69, 0
	s_add_u32 s70, s70, 0x80
	s_addc_u32 s71, s71, 0
	ds_read_b128 v[64:67], v210 offset:16384
	v_mfma_f32_32x32x16_bf16 v[48:63], v[80:83], v[88:91], v[48:63]
	ds_read_b128 v[68:71], v210 offset:20480
	v_mfma_f32_32x32x16_bf16 v[32:47], v[80:83], v[92:95], v[32:47]
	ds_read_b128 v[72:75], v214 offset:49152
	v_mfma_f32_32x32x16_bf16 v[16:31], v[84:87], v[88:91], v[16:31]
	ds_read_b128 v[76:79], v214 offset:53248
	v_mfma_f32_32x32x16_bf16 v[0:15], v[84:87], v[92:95], v[0:15]
	ds_read_b128 v[80:83], v211 offset:16384
	v_mfma_f32_32x32x16_bf16 v[48:63], v[96:99], v[104:107], v[48:63]
	ds_read_b128 v[84:87], v211 offset:20480
	v_mfma_f32_32x32x16_bf16 v[32:47], v[96:99], v[108:111], v[32:47]
	ds_read_b128 v[88:91], v215 offset:49152
	v_mfma_f32_32x32x16_bf16 v[16:31], v[100:103], v[104:107], v[16:31]
	ds_read_b128 v[92:95], v215 offset:53248
	v_mfma_f32_32x32x16_bf16 v[0:15], v[100:103], v[108:111], v[0:15]
	ds_read_b128 v[96:99], v212 offset:16384
	v_mfma_f32_32x32x16_bf16 v[48:63], v[112:115], v[120:123], v[48:63]
	ds_read_b128 v[100:103], v212 offset:20480
	v_mfma_f32_32x32x16_bf16 v[32:47], v[112:115], v[124:127], v[32:47]
	ds_read_b128 v[104:107], v216 offset:49152
	v_mfma_f32_32x32x16_bf16 v[16:31], v[116:119], v[120:123], v[16:31]
	ds_read_b128 v[108:111], v216 offset:53248
	v_mfma_f32_32x32x16_bf16 v[0:15], v[116:119], v[124:127], v[0:15]
	s_branch .Lgm_join0_B
.Lgm_nodma0_B:
	ds_read_b128 v[64:67], v210 offset:16384
	v_mfma_f32_32x32x16_bf16 v[48:63], v[80:83], v[88:91], v[48:63]
	ds_read_b128 v[68:71], v210 offset:20480
	v_mfma_f32_32x32x16_bf16 v[32:47], v[80:83], v[92:95], v[32:47]
	ds_read_b128 v[72:75], v214 offset:49152
	v_mfma_f32_32x32x16_bf16 v[16:31], v[84:87], v[88:91], v[16:31]
	ds_read_b128 v[76:79], v214 offset:53248
	v_mfma_f32_32x32x16_bf16 v[0:15], v[84:87], v[92:95], v[0:15]
	ds_read_b128 v[80:83], v211 offset:16384
	v_mfma_f32_32x32x16_bf16 v[48:63], v[96:99], v[104:107], v[48:63]
	ds_read_b128 v[84:87], v211 offset:20480
	v_mfma_f32_32x32x16_bf16 v[32:47], v[96:99], v[108:111], v[32:47]
	ds_read_b128 v[88:91], v215 offset:49152
	v_mfma_f32_32x32x16_bf16 v[16:31], v[100:103], v[104:107], v[16:31]
	ds_read_b128 v[92:95], v215 offset:53248
	v_mfma_f32_32x32x16_bf16 v[0:15], v[100:103], v[108:111], v[0:15]
	ds_read_b128 v[96:99], v212 offset:16384
	v_mfma_f32_32x32x16_bf16 v[48:63], v[112:115], v[120:123], v[48:63]
	ds_read_b128 v[100:103], v212 offset:20480
	v_mfma_f32_32x32x16_bf16 v[32:47], v[112:115], v[124:127], v[32:47]
	ds_read_b128 v[104:107], v216 offset:49152
	v_mfma_f32_32x32x16_bf16 v[16:31], v[116:119], v[120:123], v[16:31]
	ds_read_b128 v[108:111], v216 offset:53248
	v_mfma_f32_32x32x16_bf16 v[0:15], v[116:119], v[124:127], v[0:15]
.Lgm_join0_B:
	ds_read_b128 v[112:115], v213 offset:16384
	ds_read_b128 v[116:119], v213 offset:20480
	ds_read_b128 v[120:123], v217 offset:49152
	ds_read_b128 v[124:127], v217 offset:53248
	s_waitcnt lgkmcnt(12)
	v_mfma_f32_32x32x16_bf16 v[48:63], v[64:67], v[72:75], v[48:63]
	v_mfma_f32_32x32x16_bf16 v[32:47], v[64:67], v[76:79], v[32:47]
	v_mfma_f32_32x32x16_bf16 v[16:31], v[68:71], v[72:75], v[16:31]
	v_mfma_f32_32x32x16_bf16 v[0:15], v[68:71], v[76:79], v[0:15]
	s_waitcnt vmcnt(0) lgkmcnt(0)
	s_barrier
	s_cmp_lt_u32 s64, 30
	s_cbranch_scc0 .Lgm_nodma1_B
	s_add_u32 m0, s65, 0x4000
	s_nop 0
	global_load_lds_dwordx4 v206, s[68:69]
	s_add_u32 m0, s65, 0x5000
	s_nop 0
	global_load_lds_dwordx4 v207, s[68:69]
	s_add_u32 m0, s65, 0x6000
	s_nop 0
	global_load_lds_dwordx4 v208, s[68:69]
	s_add_u32 m0, s65, 0x7000
	s_nop 0
	global_load_lds_dwordx4 v209, s[68:69]
	s_add_u32 m0, s65, 0xc000
	s_nop 0
	global_load_lds_dwordx4 v206, s[70:71]
	s_add_u32 m0, s65, 0xd000
	s_nop 0
	global_load_lds_dwordx4 v207, s[70:71]
	s_add_u32 m0, s65, 0xe000
	s_nop 0
	global_load_lds_dwordx4 v208, s[70:71]
	s_add_u32 m0, s65, 0xf000
	s_nop 0
	global_load_lds_dwordx4 v209, s[70:71]
	s_add_u32 s68, s68, 0x80
	s_addc_u32 s69, s69, 0
	s_add_u32 s70, s70, 0x80
	s_addc_u32 s71, s71, 0
	ds_read_b128 v[64:67], v210 offset:0
	v_mfma_f32_32x32x16_bf16 v[48:63], v[80:83], v[88:91], v[48:63]
	ds_read_b128 v[68:71], v210 offset:4096
	v_mfma_f32_32x32x16_bf16 v[32:47], v[80:83], v[92:95], v[32:47]
	ds_read_b128 v[72:75], v214 offset:32768
	v_mfma_f32_32x32x16_bf16 v[16:31], v[84:87], v[88:91], v[16:31]
	ds_read_b128 v[76:79], v214 offset:36864
	v_mfma_f32_32x32x16_bf16 v[0:15], v[84:87], v[92:95], v[0:15]
	ds_read_b128 v[80:83], v211 offset:0
	v_mfma_f32_32x32x16_bf16 v[48:63], v[96:99], v[104:107], v[48:63]
	ds_read_b128 v[84:87], v211 offset:4096
	v_mfma_f32_32x32x16_bf16 v[32:47], v[96:99], v[108:111], v[32:47]
	ds_read_b128 v[88:91], v215 offset:32768
	v_mfma_f32_32x32x16_bf16 v[16:31], v[100:103], v[104:107], v[16:31]
	ds_read_b128 v[92:95], v215 offset:36864
	v_mfma_f32_32x32x16_bf16 v[0:15], v[100:103], v[108:111], v[0:15]
	ds_read_b128 v[96:99], v212 offset:0
	v_mfma_f32_32x32x16_bf16 v[48:63], v[112:115], v[120:123], v[48:63]
	ds_read_b128 v[100:103], v212 offset:4096
	v_mfma_f32_32x32x16_bf16 v[32:47], v[112:115], v[124:127], v[32:47]
	ds_read_b128 v[104:107], v216 offset:32768
	v_mfma_f32_32x32x16_bf16 v[16:31], v[116:119], v[120:123], v[16:31]
	ds_read_b128 v[108:111], v216 offset:36864
	v_mfma_f32_32x32x16_bf16 v[0:15], v[116:119], v[124:127], v[0:15]
	s_branch .Lgm_join1_B
.Lgm_nodma1_B:
	ds_read_b128 v[64:67], v210 offset:0
	v_mfma_f32_32x32x16_bf16 v[48:63], v[80:83], v[88:91], v[48:63]
	ds_read_b128 v[68:71], v210 offset:4096
	v_mfma_f32_32x32x16_bf16 v[32:47], v[80:83], v[92:95], v[32:47]
	ds_read_b128 v[72:75], v214 offset:32768
	v_mfma_f32_32x32x16_bf16 v[16:31], v[84:87], v[88:91], v[16:31]
	ds_read_b128 v[76:79], v214 offset:36864
	v_mfma_f32_32x32x16_bf16 v[0:15], v[84:87], v[92:95], v[0:15]
	ds_read_b128 v[80:83], v211 offset:0
	v_mfma_f32_32x32x16_bf16 v[48:63], v[96:99], v[104:107], v[48:63]
	ds_read_b128 v[84:87], v211 offset:4096
	v_mfma_f32_32x32x16_bf16 v[32:47], v[96:99], v[108:111], v[32:47]
	ds_read_b128 v[88:91], v215 offset:32768
	v_mfma_f32_32x32x16_bf16 v[16:31], v[100:103], v[104:107], v[16:31]
	ds_read_b128 v[92:95], v215 offset:36864
	v_mfma_f32_32x32x16_bf16 v[0:15], v[100:103], v[108:111], v[0:15]
	ds_read_b128 v[96:99], v212 offset:0
	v_mfma_f32_32x32x16_bf16 v[48:63], v[112:115], v[120:123], v[48:63]
	ds_read_b128 v[100:103], v212 offset:4096
	v_mfma_f32_32x32x16_bf16 v[32:47], v[112:115], v[124:127], v[32:47]
	ds_read_b128 v[104:107], v216 offset:32768
	v_mfma_f32_32x32x16_bf16 v[16:31], v[116:119], v[120:123], v[16:31]
	ds_read_b128 v[108:111], v216 offset:36864
	v_mfma_f32_32x32x16_bf16 v[0:15], v[116:119], v[124:127], v[0:15]

.Lgm_loop_gemmF2:
	ds_read_b128 v[234:237], v148 offset:0
	ds_read_b128 v[238:241], v148 offset:4096
	ds_read_b128 v[242:245], v149 offset:32768
	ds_read_b128 v[246:249], v149 offset:36864
	s_waitcnt lgkmcnt(12)
	v_mfma_f32_32x32x16_bf16 v[32:47], v[186:189], v[194:197], v[32:47]
	v_mfma_f32_32x32x16_bf16 v[48:63], v[186:189], v[198:201], v[48:63]
	v_mfma_f32_32x32x16_bf16 v[0:15], v[190:193], v[194:197], v[0:15]
	v_mfma_f32_32x32x16_bf16 v[16:31], v[190:193], v[198:201], v[16:31]
	s_waitcnt vmcnt(0) lgkmcnt(0)
	s_barrier
	s_cmp_lt_u32 s60, 14
	s_cbranch_scc0 .Lgm_nodma0_gemmF2
	s_add_u32 m0, s61, 0x0
	s_nop 0
	global_load_lds_dwordx4 v64, s[56:57]
	s_add_u32 m0, s61, 0x1000
	s_nop 0
	global_load_lds_dwordx4 v65, s[56:57]
	s_add_u32 m0, s61, 0x2000
	s_nop 0
	global_load_lds_dwordx4 v66, s[56:57]
	s_add_u32 m0, s61, 0x3000
	s_nop 0
	global_load_lds_dwordx4 v67, s[56:57]
	s_add_u32 m0, s61, 0x8000
	s_nop 0
	global_load_lds_dwordx4 v64, s[58:59]
	s_add_u32 m0, s61, 0x9000
	s_nop 0
	global_load_lds_dwordx4 v65, s[58:59]
	s_add_u32 m0, s61, 0xa000
	s_nop 0
	global_load_lds_dwordx4 v66, s[58:59]
	s_add_u32 m0, s61, 0xb000
	s_nop 0
	global_load_lds_dwordx4 v67, s[58:59]
	s_add_u32 s56, s56, 0x80
	s_addc_u32 s57, s57, 0
	s_add_u32 s58, s58, 0x80
	s_addc_u32 s59, s59, 0
	ds_read_b128 v[186:189], v142 offset:16384
	v_mfma_f32_32x32x16_bf16 v[32:47], v[202:205], v[210:213], v[32:47]
	ds_read_b128 v[190:193], v142 offset:20480
	v_mfma_f32_32x32x16_bf16 v[48:63], v[202:205], v[214:217], v[48:63]
	ds_read_b128 v[194:197], v143 offset:49152
	v_mfma_f32_32x32x16_bf16 v[0:15], v[206:209], v[210:213], v[0:15]
	ds_read_b128 v[198:201], v143 offset:53248
	v_mfma_f32_32x32x16_bf16 v[16:31], v[206:209], v[214:217], v[16:31]
	ds_read_b128 v[202:205], v144 offset:16384
	v_mfma_f32_32x32x16_bf16 v[32:47], v[218:221], v[226:229], v[32:47]
	ds_read_b128 v[206:209], v144 offset:20480
	v_mfma_f32_32x32x16_bf16 v[48:63], v[218:221], v[230:233], v[48:63]
	ds_read_b128 v[210:213], v145 offset:49152
	v_mfma_f32_32x32x16_bf16 v[0:15], v[222:225], v[226:229], v[0:15]
	ds_read_b128 v[214:217], v145 offset:53248
	v_mfma_f32_32x32x16_bf16 v[16:31], v[222:225], v[230:233], v[16:31]
	ds_read_b128 v[218:221], v146 offset:16384
	v_mfma_f32_32x32x16_bf16 v[32:47], v[234:237], v[242:245], v[32:47]
	ds_read_b128 v[222:225], v146 offset:20480
	v_mfma_f32_32x32x16_bf16 v[48:63], v[234:237], v[246:249], v[48:63]
	ds_read_b128 v[226:229], v147 offset:49152
	v_mfma_f32_32x32x16_bf16 v[0:15], v[238:241], v[242:245], v[0:15]
	ds_read_b128 v[230:233], v147 offset:53248
	v_mfma_f32_32x32x16_bf16 v[16:31], v[238:241], v[246:249], v[16:31]
	s_branch .Lgm_join0_gemmF2
.Lgm_nodma0_gemmF2:
	ds_read_b128 v[186:189], v142 offset:16384
	v_mfma_f32_32x32x16_bf16 v[32:47], v[202:205], v[210:213], v[32:47]
	ds_read_b128 v[190:193], v142 offset:20480
	v_mfma_f32_32x32x16_bf16 v[48:63], v[202:205], v[214:217], v[48:63]
	ds_read_b128 v[194:197], v143 offset:49152
	v_mfma_f32_32x32x16_bf16 v[0:15], v[206:209], v[210:213], v[0:15]
	ds_read_b128 v[198:201], v143 offset:53248
	v_mfma_f32_32x32x16_bf16 v[16:31], v[206:209], v[214:217], v[16:31]
	ds_read_b128 v[202:205], v144 offset:16384
	v_mfma_f32_32x32x16_bf16 v[32:47], v[218:221], v[226:229], v[32:47]
	ds_read_b128 v[206:209], v144 offset:20480
	v_mfma_f32_32x32x16_bf16 v[48:63], v[218:221], v[230:233], v[48:63]
	ds_read_b128 v[210:213], v145 offset:49152
	v_mfma_f32_32x32x16_bf16 v[0:15], v[222:225], v[226:229], v[0:15]
	ds_read_b128 v[214:217], v145 offset:53248
	v_mfma_f32_32x32x16_bf16 v[16:31], v[222:225], v[230:233], v[16:31]
	ds_read_b128 v[218:221], v146 offset:16384
	v_mfma_f32_32x32x16_bf16 v[32:47], v[234:237], v[242:245], v[32:47]
	ds_read_b128 v[222:225], v146 offset:20480
	v_mfma_f32_32x32x16_bf16 v[48:63], v[234:237], v[246:249], v[48:63]
	ds_read_b128 v[226:229], v147 offset:49152
	v_mfma_f32_32x32x16_bf16 v[0:15], v[238:241], v[242:245], v[0:15]
	ds_read_b128 v[230:233], v147 offset:53248
	v_mfma_f32_32x32x16_bf16 v[16:31], v[238:241], v[246:249], v[16:31]
.Lgm_join0_gemmF2:
	ds_read_b128 v[234:237], v148 offset:16384
	ds_read_b128 v[238:241], v148 offset:20480
	ds_read_b128 v[242:245], v149 offset:49152
	ds_read_b128 v[246:249], v149 offset:53248
	s_waitcnt lgkmcnt(12)
	v_mfma_f32_32x32x16_bf16 v[32:47], v[186:189], v[194:197], v[32:47]
	v_mfma_f32_32x32x16_bf16 v[48:63], v[186:189], v[198:201], v[48:63]
	v_mfma_f32_32x32x16_bf16 v[0:15], v[190:193], v[194:197], v[0:15]
	v_mfma_f32_32x32x16_bf16 v[16:31], v[190:193], v[198:201], v[16:31]
	s_waitcnt vmcnt(0) lgkmcnt(0)
	s_barrier
	s_cmp_lt_u32 s60, 14
	s_cbranch_scc0 .Lgm_nodma1_gemmF2
	s_add_u32 m0, s61, 0x4000
	s_nop 0
	global_load_lds_dwordx4 v64, s[56:57]
	s_add_u32 m0, s61, 0x5000
	s_nop 0
	global_load_lds_dwordx4 v65, s[56:57]
	s_add_u32 m0, s61, 0x6000
	s_nop 0
	global_load_lds_dwordx4 v66, s[56:57]
	s_add_u32 m0, s61, 0x7000
	s_nop 0
	global_load_lds_dwordx4 v67, s[56:57]
	s_add_u32 m0, s61, 0xc000
	s_nop 0
	global_load_lds_dwordx4 v64, s[58:59]
	s_add_u32 m0, s61, 0xd000
	s_nop 0
	global_load_lds_dwordx4 v65, s[58:59]
	s_add_u32 m0, s61, 0xe000
	s_nop 0
	global_load_lds_dwordx4 v66, s[58:59]
	s_add_u32 m0, s61, 0xf000
	s_nop 0
	global_load_lds_dwordx4 v67, s[58:59]
	s_add_u32 s56, s56, 0x80
	s_addc_u32 s57, s57, 0
	s_add_u32 s58, s58, 0x80
	s_addc_u32 s59, s59, 0
	ds_read_b128 v[186:189], v142 offset:0
	v_mfma_f32_32x32x16_bf16 v[32:47], v[202:205], v[210:213], v[32:47]
	ds_read_b128 v[190:193], v142 offset:4096
	v_mfma_f32_32x32x16_bf16 v[48:63], v[202:205], v[214:217], v[48:63]
	ds_read_b128 v[194:197], v143 offset:32768
	v_mfma_f32_32x32x16_bf16 v[0:15], v[206:209], v[210:213], v[0:15]
	ds_read_b128 v[198:201], v143 offset:36864
	v_mfma_f32_32x32x16_bf16 v[16:31], v[206:209], v[214:217], v[16:31]
	ds_read_b128 v[202:205], v144 offset:0
	v_mfma_f32_32x32x16_bf16 v[32:47], v[218:221], v[226:229], v[32:47]
	ds_read_b128 v[206:209], v144 offset:4096
	v_mfma_f32_32x32x16_bf16 v[48:63], v[218:221], v[230:233], v[48:63]
	ds_read_b128 v[210:213], v145 offset:32768
	v_mfma_f32_32x32x16_bf16 v[0:15], v[222:225], v[226:229], v[0:15]
	ds_read_b128 v[214:217], v145 offset:36864
	v_mfma_f32_32x32x16_bf16 v[16:31], v[222:225], v[230:233], v[16:31]
	ds_read_b128 v[218:221], v146 offset:0
	v_mfma_f32_32x32x16_bf16 v[32:47], v[234:237], v[242:245], v[32:47]
	ds_read_b128 v[222:225], v146 offset:4096
	v_mfma_f32_32x32x16_bf16 v[48:63], v[234:237], v[246:249], v[48:63]
	ds_read_b128 v[226:229], v147 offset:32768
	v_mfma_f32_32x32x16_bf16 v[0:15], v[238:241], v[242:245], v[0:15]
	ds_read_b128 v[230:233], v147 offset:36864
	v_mfma_f32_32x32x16_bf16 v[16:31], v[238:241], v[246:249], v[16:31]
	s_branch .Lgm_join1_gemmF2
.Lgm_nodma1_gemmF2:
	ds_read_b128 v[186:189], v142 offset:0
	v_mfma_f32_32x32x16_bf16 v[32:47], v[202:205], v[210:213], v[32:47]
	ds_read_b128 v[190:193], v142 offset:4096
	v_mfma_f32_32x32x16_bf16 v[48:63], v[202:205], v[214:217], v[48:63]
	ds_read_b128 v[194:197], v143 offset:32768
	v_mfma_f32_32x32x16_bf16 v[0:15], v[206:209], v[210:213], v[0:15]
	ds_read_b128 v[198:201], v143 offset:36864
	v_mfma_f32_32x32x16_bf16 v[16:31], v[206:209], v[214:217], v[16:31]
	ds_read_b128 v[202:205], v144 offset:0
	v_mfma_f32_32x32x16_bf16 v[32:47], v[218:221], v[226:229], v[32:47]
	ds_read_b128 v[206:209], v144 offset:4096
	v_mfma_f32_32x32x16_bf16 v[48:63], v[218:221], v[230:233], v[48:63]
	ds_read_b128 v[210:213], v145 offset:32768
	v_mfma_f32_32x32x16_bf16 v[0:15], v[222:225], v[226:229], v[0:15]
	ds_read_b128 v[214:217], v145 offset:36864
	v_mfma_f32_32x32x16_bf16 v[16:31], v[222:225], v[230:233], v[16:31]
	ds_read_b128 v[218:221], v146 offset:0
	v_mfma_f32_32x32x16_bf16 v[32:47], v[234:237], v[242:245], v[32:47]
	ds_read_b128 v[222:225], v146 offset:4096
	v_mfma_f32_32x32x16_bf16 v[48:63], v[234:237], v[246:249], v[48:63]
	ds_read_b128 v[226:229], v147 offset:32768
	v_mfma_f32_32x32x16_bf16 v[0:15], v[238:241], v[242:245], v[0:15]
	ds_read_b128 v[230:233], v147 offset:36864
	v_mfma_f32_32x32x16_bf16 v[16:31], v[238:241], v[246:249], v[16:31]

.Lgm_loop_G:
	ds_read_b128 v[112:115], v197 offset:0
	ds_read_b128 v[116:119], v197 offset:4096
	ds_read_b128 v[120:123], v201 offset:32768
	ds_read_b128 v[124:127], v201 offset:36864
	s_waitcnt lgkmcnt(12)
	v_mfma_f32_32x32x16_bf16 v[48:63], v[64:67], v[72:75], v[48:63]
	v_mfma_f32_32x32x16_bf16 v[32:47], v[64:67], v[76:79], v[32:47]
	v_mfma_f32_32x32x16_bf16 v[16:31], v[68:71], v[72:75], v[16:31]
	v_mfma_f32_32x32x16_bf16 v[0:15], v[68:71], v[76:79], v[0:15]
	s_waitcnt vmcnt(0) lgkmcnt(0)
	s_barrier
	s_cmp_lt_u32 s6, 30
	s_cbranch_scc0 .Lgm_nodma0_G
	s_add_u32 m0, s25, 0x0
	s_nop 0
	global_load_lds_dwordx4 v190, s[16:17]
	s_add_u32 m0, s25, 0x1000
	s_nop 0
	global_load_lds_dwordx4 v191, s[16:17]
	s_add_u32 m0, s25, 0x2000
	s_nop 0
	global_load_lds_dwordx4 v192, s[16:17]
	s_add_u32 m0, s25, 0x3000
	s_nop 0
	global_load_lds_dwordx4 v193, s[16:17]
	s_add_u32 m0, s25, 0x8000
	s_nop 0
	global_load_lds_dwordx4 v190, s[20:21]
	s_add_u32 m0, s25, 0x9000
	s_nop 0
	global_load_lds_dwordx4 v191, s[20:21]
	s_add_u32 m0, s25, 0xa000
	s_nop 0
	global_load_lds_dwordx4 v192, s[20:21]
	s_add_u32 m0, s25, 0xb000
	s_nop 0
	global_load_lds_dwordx4 v193, s[20:21]
	s_add_u32 s16, s16, 0x80
	s_addc_u32 s17, s17, 0
	s_add_u32 s20, s20, 0x80
	s_addc_u32 s21, s21, 0
	ds_read_b128 v[64:67], v194 offset:16384
	v_mfma_f32_32x32x16_bf16 v[48:63], v[80:83], v[88:91], v[48:63]
	ds_read_b128 v[68:71], v194 offset:20480
	v_mfma_f32_32x32x16_bf16 v[32:47], v[80:83], v[92:95], v[32:47]
	ds_read_b128 v[72:75], v198 offset:49152
	v_mfma_f32_32x32x16_bf16 v[16:31], v[84:87], v[88:91], v[16:31]
	ds_read_b128 v[76:79], v198 offset:53248
	v_mfma_f32_32x32x16_bf16 v[0:15], v[84:87], v[92:95], v[0:15]
	ds_read_b128 v[80:83], v195 offset:16384
	v_mfma_f32_32x32x16_bf16 v[48:63], v[96:99], v[104:107], v[48:63]
	ds_read_b128 v[84:87], v195 offset:20480
	v_mfma_f32_32x32x16_bf16 v[32:47], v[96:99], v[108:111], v[32:47]
	ds_read_b128 v[88:91], v199 offset:49152
	v_mfma_f32_32x32x16_bf16 v[16:31], v[100:103], v[104:107], v[16:31]
	ds_read_b128 v[92:95], v199 offset:53248
	v_mfma_f32_32x32x16_bf16 v[0:15], v[100:103], v[108:111], v[0:15]
	ds_read_b128 v[96:99], v196 offset:16384
	v_mfma_f32_32x32x16_bf16 v[48:63], v[112:115], v[120:123], v[48:63]
	ds_read_b128 v[100:103], v196 offset:20480
	v_mfma_f32_32x32x16_bf16 v[32:47], v[112:115], v[124:127], v[32:47]
	ds_read_b128 v[104:107], v200 offset:49152
	v_mfma_f32_32x32x16_bf16 v[16:31], v[116:119], v[120:123], v[16:31]
	ds_read_b128 v[108:111], v200 offset:53248
	v_mfma_f32_32x32x16_bf16 v[0:15], v[116:119], v[124:127], v[0:15]
	s_branch .Lgm_join0_G
.Lgm_nodma0_G:
	ds_read_b128 v[64:67], v194 offset:16384
	v_mfma_f32_32x32x16_bf16 v[48:63], v[80:83], v[88:91], v[48:63]
	ds_read_b128 v[68:71], v194 offset:20480
	v_mfma_f32_32x32x16_bf16 v[32:47], v[80:83], v[92:95], v[32:47]
	ds_read_b128 v[72:75], v198 offset:49152
	v_mfma_f32_32x32x16_bf16 v[16:31], v[84:87], v[88:91], v[16:31]
	ds_read_b128 v[76:79], v198 offset:53248
	v_mfma_f32_32x32x16_bf16 v[0:15], v[84:87], v[92:95], v[0:15]
	ds_read_b128 v[80:83], v195 offset:16384
	v_mfma_f32_32x32x16_bf16 v[48:63], v[96:99], v[104:107], v[48:63]
	ds_read_b128 v[84:87], v195 offset:20480
	v_mfma_f32_32x32x16_bf16 v[32:47], v[96:99], v[108:111], v[32:47]
	ds_read_b128 v[88:91], v199 offset:49152
	v_mfma_f32_32x32x16_bf16 v[16:31], v[100:103], v[104:107], v[16:31]
	ds_read_b128 v[92:95], v199 offset:53248
	v_mfma_f32_32x32x16_bf16 v[0:15], v[100:103], v[108:111], v[0:15]
	ds_read_b128 v[96:99], v196 offset:16384
	v_mfma_f32_32x32x16_bf16 v[48:63], v[112:115], v[120:123], v[48:63]
	ds_read_b128 v[100:103], v196 offset:20480
	v_mfma_f32_32x32x16_bf16 v[32:47], v[112:115], v[124:127], v[32:47]
	ds_read_b128 v[104:107], v200 offset:49152
	v_mfma_f32_32x32x16_bf16 v[16:31], v[116:119], v[120:123], v[16:31]
	ds_read_b128 v[108:111], v200 offset:53248
	v_mfma_f32_32x32x16_bf16 v[0:15], v[116:119], v[124:127], v[0:15]
.Lgm_join0_G:
	ds_read_b128 v[112:115], v197 offset:16384
	ds_read_b128 v[116:119], v197 offset:20480
	ds_read_b128 v[120:123], v201 offset:49152
	ds_read_b128 v[124:127], v201 offset:53248
	s_waitcnt lgkmcnt(12)
	v_mfma_f32_32x32x16_bf16 v[48:63], v[64:67], v[72:75], v[48:63]
	v_mfma_f32_32x32x16_bf16 v[32:47], v[64:67], v[76:79], v[32:47]
	v_mfma_f32_32x32x16_bf16 v[16:31], v[68:71], v[72:75], v[16:31]
	v_mfma_f32_32x32x16_bf16 v[0:15], v[68:71], v[76:79], v[0:15]
	s_waitcnt vmcnt(0) lgkmcnt(0)
	s_barrier
	s_cmp_lt_u32 s6, 30
	s_cbranch_scc0 .Lgm_nodma1_G
	s_add_u32 m0, s25, 0x4000
	s_nop 0
	global_load_lds_dwordx4 v190, s[16:17]
	s_add_u32 m0, s25, 0x5000
	s_nop 0
	global_load_lds_dwordx4 v191, s[16:17]
	s_add_u32 m0, s25, 0x6000
	s_nop 0
	global_load_lds_dwordx4 v192, s[16:17]
	s_add_u32 m0, s25, 0x7000
	s_nop 0
	global_load_lds_dwordx4 v193, s[16:17]
	s_add_u32 m0, s25, 0xc000
	s_nop 0
	global_load_lds_dwordx4 v190, s[20:21]
	s_add_u32 m0, s25, 0xd000
	s_nop 0
	global_load_lds_dwordx4 v191, s[20:21]
	s_add_u32 m0, s25, 0xe000
	s_nop 0
	global_load_lds_dwordx4 v192, s[20:21]
	s_add_u32 m0, s25, 0xf000
	s_nop 0
	global_load_lds_dwordx4 v193, s[20:21]
	s_add_u32 s16, s16, 0x80
	s_addc_u32 s17, s17, 0
	s_add_u32 s20, s20, 0x80
	s_addc_u32 s21, s21, 0
	ds_read_b128 v[64:67], v194 offset:0
	v_mfma_f32_32x32x16_bf16 v[48:63], v[80:83], v[88:91], v[48:63]
	ds_read_b128 v[68:71], v194 offset:4096
	v_mfma_f32_32x32x16_bf16 v[32:47], v[80:83], v[92:95], v[32:47]
	ds_read_b128 v[72:75], v198 offset:32768
	v_mfma_f32_32x32x16_bf16 v[16:31], v[84:87], v[88:91], v[16:31]
	ds_read_b128 v[76:79], v198 offset:36864
	v_mfma_f32_32x32x16_bf16 v[0:15], v[84:87], v[92:95], v[0:15]
	ds_read_b128 v[80:83], v195 offset:0
	v_mfma_f32_32x32x16_bf16 v[48:63], v[96:99], v[104:107], v[48:63]
	ds_read_b128 v[84:87], v195 offset:4096
	v_mfma_f32_32x32x16_bf16 v[32:47], v[96:99], v[108:111], v[32:47]
	ds_read_b128 v[88:91], v199 offset:32768
	v_mfma_f32_32x32x16_bf16 v[16:31], v[100:103], v[104:107], v[16:31]
	ds_read_b128 v[92:95], v199 offset:36864
	v_mfma_f32_32x32x16_bf16 v[0:15], v[100:103], v[108:111], v[0:15]
	ds_read_b128 v[96:99], v196 offset:0
	v_mfma_f32_32x32x16_bf16 v[48:63], v[112:115], v[120:123], v[48:63]
	ds_read_b128 v[100:103], v196 offset:4096
	v_mfma_f32_32x32x16_bf16 v[32:47], v[112:115], v[124:127], v[32:47]
	ds_read_b128 v[104:107], v200 offset:32768
	v_mfma_f32_32x32x16_bf16 v[16:31], v[116:119], v[120:123], v[16:31]
	ds_read_b128 v[108:111], v200 offset:36864
	v_mfma_f32_32x32x16_bf16 v[0:15], v[116:119], v[124:127], v[0:15]
	s_branch .Lgm_join1_G
.Lgm_nodma1_G:
	ds_read_b128 v[64:67], v194 offset:0
	v_mfma_f32_32x32x16_bf16 v[48:63], v[80:83], v[88:91], v[48:63]
	ds_read_b128 v[68:71], v194 offset:4096
	v_mfma_f32_32x32x16_bf16 v[32:47], v[80:83], v[92:95], v[32:47]
	ds_read_b128 v[72:75], v198 offset:32768
	v_mfma_f32_32x32x16_bf16 v[16:31], v[84:87], v[88:91], v[16:31]
	ds_read_b128 v[76:79], v198 offset:36864
	v_mfma_f32_32x32x16_bf16 v[0:15], v[84:87], v[92:95], v[0:15]
	ds_read_b128 v[80:83], v195 offset:0
	v_mfma_f32_32x32x16_bf16 v[48:63], v[96:99], v[104:107], v[48:63]
	ds_read_b128 v[84:87], v195 offset:4096
	v_mfma_f32_32x32x16_bf16 v[32:47], v[96:99], v[108:111], v[32:47]
	ds_read_b128 v[88:91], v199 offset:32768
	v_mfma_f32_32x32x16_bf16 v[16:31], v[100:103], v[104:107], v[16:31]
	ds_read_b128 v[92:95], v199 offset:36864
	v_mfma_f32_32x32x16_bf16 v[0:15], v[100:103], v[108:111], v[0:15]
	ds_read_b128 v[96:99], v196 offset:0
	v_mfma_f32_32x32x16_bf16 v[48:63], v[112:115], v[120:123], v[48:63]
	ds_read_b128 v[100:103], v196 offset:4096
	v_mfma_f32_32x32x16_bf16 v[32:47], v[112:115], v[124:127], v[32:47]
	ds_read_b128 v[104:107], v200 offset:32768
	v_mfma_f32_32x32x16_bf16 v[16:31], v[116:119], v[120:123], v[16:31]
	ds_read_b128 v[108:111], v200 offset:36864
	v_mfma_f32_32x32x16_bf16 v[0:15], v[116:119], v[124:127], v[0:15]

.Lgm_loop_H:
	ds_read_b128 v[112:115], v185 offset:0
	ds_read_b128 v[116:119], v185 offset:4096
	ds_read_b128 v[120:123], v186 offset:32768
	ds_read_b128 v[124:127], v186 offset:36864
	s_waitcnt lgkmcnt(12)
	v_mfma_f32_32x32x16_bf16 v[48:63], v[64:67], v[72:75], v[48:63]
	v_mfma_f32_32x32x16_bf16 v[32:47], v[64:67], v[76:79], v[32:47]
	v_mfma_f32_32x32x16_bf16 v[16:31], v[68:71], v[72:75], v[16:31]
	v_mfma_f32_32x32x16_bf16 v[0:15], v[68:71], v[76:79], v[0:15]
	s_waitcnt vmcnt(0) lgkmcnt(0)
	s_barrier
	s_cmp_lt_u32 s12, 30
	s_cbranch_scc0 .Lgm_nodma0_H
	s_add_u32 m0, s36, 0x0
	s_nop 0
	global_load_lds_dwordx4 v188, s[16:17]
	s_add_u32 m0, s36, 0x1000
	s_nop 0
	global_load_lds_dwordx4 v189, s[16:17]
	s_add_u32 m0, s36, 0x2000
	s_nop 0
	global_load_lds_dwordx4 v190, s[16:17]
	s_add_u32 m0, s36, 0x3000
	s_nop 0
	global_load_lds_dwordx4 v191, s[16:17]
	s_add_u32 m0, s36, 0x8000
	s_nop 0
	global_load_lds_dwordx4 v188, s[34:35]
	s_add_u32 m0, s36, 0x9000
	s_nop 0
	global_load_lds_dwordx4 v189, s[34:35]
	s_add_u32 m0, s36, 0xa000
	s_nop 0
	global_load_lds_dwordx4 v190, s[34:35]
	s_add_u32 m0, s36, 0xb000
	s_nop 0
	global_load_lds_dwordx4 v191, s[34:35]
	s_add_u32 s16, s16, 0x80
	s_addc_u32 s17, s17, 0
	s_add_u32 s34, s34, 0x80
	s_addc_u32 s35, s35, 0
	ds_read_b128 v[64:67], v177 offset:16384
	v_mfma_f32_32x32x16_bf16 v[48:63], v[80:83], v[88:91], v[48:63]
	ds_read_b128 v[68:71], v177 offset:20480
	v_mfma_f32_32x32x16_bf16 v[32:47], v[80:83], v[92:95], v[32:47]
	ds_read_b128 v[72:75], v178 offset:49152
	v_mfma_f32_32x32x16_bf16 v[16:31], v[84:87], v[88:91], v[16:31]
	ds_read_b128 v[76:79], v178 offset:53248
	v_mfma_f32_32x32x16_bf16 v[0:15], v[84:87], v[92:95], v[0:15]
	ds_read_b128 v[80:83], v179 offset:16384
	v_mfma_f32_32x32x16_bf16 v[48:63], v[96:99], v[104:107], v[48:63]
	ds_read_b128 v[84:87], v179 offset:20480
	v_mfma_f32_32x32x16_bf16 v[32:47], v[96:99], v[108:111], v[32:47]
	ds_read_b128 v[88:91], v182 offset:49152
	v_mfma_f32_32x32x16_bf16 v[16:31], v[100:103], v[104:107], v[16:31]
	ds_read_b128 v[92:95], v182 offset:53248
	v_mfma_f32_32x32x16_bf16 v[0:15], v[100:103], v[108:111], v[0:15]
	ds_read_b128 v[96:99], v183 offset:16384
	v_mfma_f32_32x32x16_bf16 v[48:63], v[112:115], v[120:123], v[48:63]
	ds_read_b128 v[100:103], v183 offset:20480
	v_mfma_f32_32x32x16_bf16 v[32:47], v[112:115], v[124:127], v[32:47]
	ds_read_b128 v[104:107], v184 offset:49152
	v_mfma_f32_32x32x16_bf16 v[16:31], v[116:119], v[120:123], v[16:31]
	ds_read_b128 v[108:111], v184 offset:53248
	v_mfma_f32_32x32x16_bf16 v[0:15], v[116:119], v[124:127], v[0:15]
	s_branch .Lgm_join0_H
.Lgm_nodma0_H:
	ds_read_b128 v[64:67], v177 offset:16384
	v_mfma_f32_32x32x16_bf16 v[48:63], v[80:83], v[88:91], v[48:63]
	ds_read_b128 v[68:71], v177 offset:20480
	v_mfma_f32_32x32x16_bf16 v[32:47], v[80:83], v[92:95], v[32:47]
	ds_read_b128 v[72:75], v178 offset:49152
	v_mfma_f32_32x32x16_bf16 v[16:31], v[84:87], v[88:91], v[16:31]
	ds_read_b128 v[76:79], v178 offset:53248
	v_mfma_f32_32x32x16_bf16 v[0:15], v[84:87], v[92:95], v[0:15]
	ds_read_b128 v[80:83], v179 offset:16384
	v_mfma_f32_32x32x16_bf16 v[48:63], v[96:99], v[104:107], v[48:63]
	ds_read_b128 v[84:87], v179 offset:20480
	v_mfma_f32_32x32x16_bf16 v[32:47], v[96:99], v[108:111], v[32:47]
	ds_read_b128 v[88:91], v182 offset:49152
	v_mfma_f32_32x32x16_bf16 v[16:31], v[100:103], v[104:107], v[16:31]
	ds_read_b128 v[92:95], v182 offset:53248
	v_mfma_f32_32x32x16_bf16 v[0:15], v[100:103], v[108:111], v[0:15]
	ds_read_b128 v[96:99], v183 offset:16384
	v_mfma_f32_32x32x16_bf16 v[48:63], v[112:115], v[120:123], v[48:63]
	ds_read_b128 v[100:103], v183 offset:20480
	v_mfma_f32_32x32x16_bf16 v[32:47], v[112:115], v[124:127], v[32:47]
	ds_read_b128 v[104:107], v184 offset:49152
	v_mfma_f32_32x32x16_bf16 v[16:31], v[116:119], v[120:123], v[16:31]
	ds_read_b128 v[108:111], v184 offset:53248
	v_mfma_f32_32x32x16_bf16 v[0:15], v[116:119], v[124:127], v[0:15]
.Lgm_join0_H:
	ds_read_b128 v[112:115], v185 offset:16384
	ds_read_b128 v[116:119], v185 offset:20480
	ds_read_b128 v[120:123], v186 offset:49152
	ds_read_b128 v[124:127], v186 offset:53248
	s_waitcnt lgkmcnt(12)
	v_mfma_f32_32x32x16_bf16 v[48:63], v[64:67], v[72:75], v[48:63]
	v_mfma_f32_32x32x16_bf16 v[32:47], v[64:67], v[76:79], v[32:47]
	v_mfma_f32_32x32x16_bf16 v[16:31], v[68:71], v[72:75], v[16:31]
	v_mfma_f32_32x32x16_bf16 v[0:15], v[68:71], v[76:79], v[0:15]
	s_waitcnt vmcnt(0) lgkmcnt(0)
	s_barrier
	s_cmp_lt_u32 s12, 30
	s_cbranch_scc0 .Lgm_nodma1_H
	s_add_u32 m0, s36, 0x4000
	s_nop 0
	global_load_lds_dwordx4 v188, s[16:17]
	s_add_u32 m0, s36, 0x5000
	s_nop 0
	global_load_lds_dwordx4 v189, s[16:17]
	s_add_u32 m0, s36, 0x6000
	s_nop 0
	global_load_lds_dwordx4 v190, s[16:17]
	s_add_u32 m0, s36, 0x7000
	s_nop 0
	global_load_lds_dwordx4 v191, s[16:17]
	s_add_u32 m0, s36, 0xc000
	s_nop 0
	global_load_lds_dwordx4 v188, s[34:35]
	s_add_u32 m0, s36, 0xd000
	s_nop 0
	global_load_lds_dwordx4 v189, s[34:35]
	s_add_u32 m0, s36, 0xe000
	s_nop 0
	global_load_lds_dwordx4 v190, s[34:35]
	s_add_u32 m0, s36, 0xf000
	s_nop 0
	global_load_lds_dwordx4 v191, s[34:35]
	s_add_u32 s16, s16, 0x80
	s_addc_u32 s17, s17, 0
	s_add_u32 s34, s34, 0x80
	s_addc_u32 s35, s35, 0
	ds_read_b128 v[64:67], v177 offset:0
	v_mfma_f32_32x32x16_bf16 v[48:63], v[80:83], v[88:91], v[48:63]
	ds_read_b128 v[68:71], v177 offset:4096
	v_mfma_f32_32x32x16_bf16 v[32:47], v[80:83], v[92:95], v[32:47]
	ds_read_b128 v[72:75], v178 offset:32768
	v_mfma_f32_32x32x16_bf16 v[16:31], v[84:87], v[88:91], v[16:31]
	ds_read_b128 v[76:79], v178 offset:36864
	v_mfma_f32_32x32x16_bf16 v[0:15], v[84:87], v[92:95], v[0:15]
	ds_read_b128 v[80:83], v179 offset:0
	v_mfma_f32_32x32x16_bf16 v[48:63], v[96:99], v[104:107], v[48:63]
	ds_read_b128 v[84:87], v179 offset:4096
	v_mfma_f32_32x32x16_bf16 v[32:47], v[96:99], v[108:111], v[32:47]
	ds_read_b128 v[88:91], v182 offset:32768
	v_mfma_f32_32x32x16_bf16 v[16:31], v[100:103], v[104:107], v[16:31]
	ds_read_b128 v[92:95], v182 offset:36864
	v_mfma_f32_32x32x16_bf16 v[0:15], v[100:103], v[108:111], v[0:15]
	ds_read_b128 v[96:99], v183 offset:0
	v_mfma_f32_32x32x16_bf16 v[48:63], v[112:115], v[120:123], v[48:63]
	ds_read_b128 v[100:103], v183 offset:4096
	v_mfma_f32_32x32x16_bf16 v[32:47], v[112:115], v[124:127], v[32:47]
	ds_read_b128 v[104:107], v184 offset:32768
	v_mfma_f32_32x32x16_bf16 v[16:31], v[116:119], v[120:123], v[16:31]
	ds_read_b128 v[108:111], v184 offset:36864
	v_mfma_f32_32x32x16_bf16 v[0:15], v[116:119], v[124:127], v[0:15]
	s_branch .Lgm_join1_H
.Lgm_nodma1_H:
	ds_read_b128 v[64:67], v177 offset:0
	v_mfma_f32_32x32x16_bf16 v[48:63], v[80:83], v[88:91], v[48:63]
	ds_read_b128 v[68:71], v177 offset:4096
	v_mfma_f32_32x32x16_bf16 v[32:47], v[80:83], v[92:95], v[32:47]
	ds_read_b128 v[72:75], v178 offset:32768
	v_mfma_f32_32x32x16_bf16 v[16:31], v[84:87], v[88:91], v[16:31]
	ds_read_b128 v[76:79], v178 offset:36864
	v_mfma_f32_32x32x16_bf16 v[0:15], v[84:87], v[92:95], v[0:15]
	ds_read_b128 v[80:83], v179 offset:0
	v_mfma_f32_32x32x16_bf16 v[48:63], v[96:99], v[104:107], v[48:63]
	ds_read_b128 v[84:87], v179 offset:4096
	v_mfma_f32_32x32x16_bf16 v[32:47], v[96:99], v[108:111], v[32:47]
	ds_read_b128 v[88:91], v182 offset:32768
	v_mfma_f32_32x32x16_bf16 v[16:31], v[100:103], v[104:107], v[16:31]
	ds_read_b128 v[92:95], v182 offset:36864
	v_mfma_f32_32x32x16_bf16 v[0:15], v[100:103], v[108:111], v[0:15]
	ds_read_b128 v[96:99], v183 offset:0
	v_mfma_f32_32x32x16_bf16 v[48:63], v[112:115], v[120:123], v[48:63]
	ds_read_b128 v[100:103], v183 offset:4096
	v_mfma_f32_32x32x16_bf16 v[32:47], v[112:115], v[124:127], v[32:47]
	ds_read_b128 v[104:107], v184 offset:32768
	v_mfma_f32_32x32x16_bf16 v[16:31], v[116:119], v[120:123], v[16:31]
	ds_read_b128 v[108:111], v184 offset:36864
	v_mfma_f32_32x32x16_bf16 v[0:15], v[116:119], v[124:127], v[0:15]
